# static priority raise (s_setprio 1) for the second co-resident workgroup during the NA attention phase
# baseline (speedup 1.0000x reference)
.LBB0_174:
	v_writelane_b32 v254, s72, 56
	s_and_b64 vcc, exec, s[0:1]
	s_nop 0
	v_writelane_b32 v254, s73, 57
	v_writelane_b32 v254, s74, 58
	v_writelane_b32 v254, s75, 59
	s_cbranch_vccz .LBB0_221
	s_bitcmp1_b32 s20, 8
	s_cbranch_scc0 .Lna_noprio
	s_setprio 1
.Lna_noprio:
	v_ashrrev_i32_e32 v0, 6, v134
	v_cmp_lt_i32_e32 vcc, 0, v0
	s_mov_b64 s[0:1], 0
	s_and_saveexec_b64 s[4:5], vcc
	s_xor_b64 s[22:23], exec, s[4:5]
	s_cbranch_execnz .LBB0_227
	s_or_saveexec_b64 s[22:23], s[22:23]
	s_waitcnt vmcnt(0)
	v_mov_b32_e32 v2, 8
	s_xor_b64 exec, exec, s[22:23]
	s_cbranch_execnz .LBB0_230

.LBB0_333:
	s_setprio 0
	s_add_i32 s74, s74, 1
	s_cmp_ge_i32 s74, s75
	s_mov_b64 s[0:1], -1
	s_cbranch_scc1 .LBB0_10
	v_readlane_b32 s4, v253, 38
	v_readlane_b32 s5, v253, 39
	s_and_b64 vcc, exec, s[4:5]
	s_cbranch_vccz .LBB0_389
	s_waitcnt vmcnt(0)
	s_waitcnt vmcnt(0) lgkmcnt(0)
	s_barrier
	s_mov_b64 s[0:1], exec
	v_readlane_b32 s4, v253, 2
	v_readlane_b32 s5, v253, 3
	s_and_b64 s[4:5], s[0:1], s[4:5]
	s_mov_b64 exec, s[4:5]
	s_cbranch_execz .LBB0_388
	v_mov_b32_e32 v0, 0x13800
	s_waitcnt vmcnt(0) expcnt(0) lgkmcnt(0)
	buffer_inv sc1
	ds_read_b32 v3, v0
	v_mov_b32_e32 v0, 0x13804
	ds_read_b32 v2, v0
	s_waitcnt lgkmcnt(1)
	v_cmp_ne_u32_e32 vcc, 0, v3
	s_cbranch_vccnz .LBB0_351
	s_mov_b32 s4, 1
	s_branch .LBB0_339
